# seam 1 acquire L1-only (every L2 was invalidated at seam 0 and each H line has one writer) + two release polls in flight at every seam
# baseline (speedup 1.0000x reference)
; __device__ __forceinline__ void own_barrier(unsigned* cnt, unsigned G) {
;     ...
;         unsigned spins = 0;
;         while (__hip_atomic_load(cnt, __ATOMIC_RELAXED, __HIP_MEMORY_SCOPE_AGENT) < target && ++spins < (1u << 22)) __builtin_amdgcn_s_sleep(1);
;         __builtin_amdgcn_fence(__ATOMIC_ACQUIRE, "agent"); asm volatile("s_waitcnt vmcnt(0)" ::: "memory");
;     }
;     __syncthreads();
.Lmid_done:
	buffer_inv sc0
	s_waitcnt vmcnt(0)
	s_mov_b64 exec, -1

; __device__ __forceinline__ void own_barrier(unsigned* cnt, unsigned G) {
;     ...
;         unsigned spins = 0;
;         while (__hip_atomic_load(cnt, __ATOMIC_RELAXED, __HIP_MEMORY_SCOPE_AGENT) < target && ++spins < (1u << 22)) __builtin_amdgcn_s_sleep(1);
;         __builtin_amdgcn_fence(__ATOMIC_ACQUIRE, "agent"); asm volatile("s_waitcnt vmcnt(0)" ::: "memory");
;     }
;     __syncthreads();
.Lseam1_wait:
	s_mov_b32 s100, 0x200000
	global_load_dword v2, v1, s[90:91] sc1
.Lseam1_poll:
	s_sleep 4
	global_load_dword v245, v1, s[90:91] sc1
	s_waitcnt vmcnt(1)
	v_cmp_eq_u32_e32 vcc, 1, v2
	s_cbranch_vccnz .Lseam1_done
	s_sleep 4
	global_load_dword v2, v1, s[90:91] sc1
	s_waitcnt vmcnt(1)
	v_cmp_eq_u32_e32 vcc, 1, v245
	s_cbranch_vccnz .Lseam1_done
	s_add_i32 s100, s100, -1
	s_cmp_lg_u32 s100, 0
	s_cbranch_scc1 .Lseam1_poll
.Lseam1_done:
	buffer_inv sc0
	s_waitcnt vmcnt(0)
	s_and_b32 s12, s92, 7
	s_branch .Lseam1_join

; __device__ __forceinline__ void own_barrier(unsigned* cnt, unsigned G) {
;     ...
;         unsigned spins = 0;
;         while (__hip_atomic_load(cnt, __ATOMIC_RELAXED, __HIP_MEMORY_SCOPE_AGENT) < target && ++spins < (1u << 22)) __builtin_amdgcn_s_sleep(1);
;         __builtin_amdgcn_fence(__ATOMIC_ACQUIRE, "agent"); asm volatile("s_waitcnt vmcnt(0)" ::: "memory");
;     }
;     __syncthreads();
.Lseam2_poll:
	s_sleep 4
	global_load_dword v245, v1, s[90:91] sc1
	s_waitcnt vmcnt(1)
	v_cmp_eq_u32_e32 vcc, 2, v2
	s_cbranch_vccnz .Lseam2_done
	s_sleep 4
	global_load_dword v2, v1, s[90:91] sc1
	s_waitcnt vmcnt(1)
	v_cmp_eq_u32_e32 vcc, 2, v245
	s_cbranch_vccnz .Lseam2_done
	s_add_i32 s100, s100, -1
	s_cmp_lg_u32 s100, 0
	s_cbranch_scc1 .Lseam2_poll

; __device__ __forceinline__ void own_barrier(unsigned* cnt, unsigned G) {
;     ...
;         unsigned spins = 0;
;         while (__hip_atomic_load(cnt, __ATOMIC_RELAXED, __HIP_MEMORY_SCOPE_AGENT) < target && ++spins < (1u << 22)) __builtin_amdgcn_s_sleep(1);
;         __builtin_amdgcn_fence(__ATOMIC_ACQUIRE, "agent"); asm volatile("s_waitcnt vmcnt(0)" ::: "memory");
;     }
;     __syncthreads();
.Lseam3_poll:
	s_sleep 4
	global_load_dword v245, v1, s[90:91] sc1
	s_waitcnt vmcnt(1)
	v_cmp_eq_u32_e32 vcc, 3, v2
	s_cbranch_vccnz .Lseam3_done
	s_sleep 4
	global_load_dword v2, v1, s[90:91] sc1
	s_waitcnt vmcnt(1)
	v_cmp_eq_u32_e32 vcc, 3, v245
	s_cbranch_vccnz .Lseam3_done
	s_add_i32 s100, s100, -1
	s_cmp_lg_u32 s100, 0
	s_cbranch_scc1 .Lseam3_poll

; __device__ __forceinline__ void own_barrier(unsigned* cnt, unsigned G) {
;     ...
;         unsigned spins = 0;
;         while (__hip_atomic_load(cnt, __ATOMIC_RELAXED, __HIP_MEMORY_SCOPE_AGENT) < target && ++spins < (1u << 22)) __builtin_amdgcn_s_sleep(1);
;         __builtin_amdgcn_fence(__ATOMIC_ACQUIRE, "agent"); asm volatile("s_waitcnt vmcnt(0)" ::: "memory");
;     }
;     __syncthreads();
.Lseam4_poll:
	s_sleep 4
	global_load_dword v245, v1, s[90:91] sc1
	s_waitcnt vmcnt(1)
	v_cmp_eq_u32_e32 vcc, 4, v2
	s_cbranch_vccnz .Lseam4_done
	s_sleep 4
	global_load_dword v2, v1, s[90:91] sc1
	s_waitcnt vmcnt(1)
	v_cmp_eq_u32_e32 vcc, 4, v245
	s_cbranch_vccnz .Lseam4_done
	s_add_i32 s100, s100, -1
	s_cmp_lg_u32 s100, 0
	s_cbranch_scc1 .Lseam4_poll

; __device__ __forceinline__ void own_barrier(unsigned* cnt, unsigned G) {
;     ...
;         unsigned spins = 0;
;         while (__hip_atomic_load(cnt, __ATOMIC_RELAXED, __HIP_MEMORY_SCOPE_AGENT) < target && ++spins < (1u << 22)) __builtin_amdgcn_s_sleep(1);
;         __builtin_amdgcn_fence(__ATOMIC_ACQUIRE, "agent"); asm volatile("s_waitcnt vmcnt(0)" ::: "memory");
;     }
;     __syncthreads();
.Lseam5_poll:
	s_sleep 4
	global_load_dword v245, v1, s[90:91] sc1
	s_waitcnt vmcnt(1)
	v_cmp_eq_u32_e32 vcc, 5, v2
	s_cbranch_vccnz .Lseam5_done
	s_sleep 4
	global_load_dword v2, v1, s[90:91] sc1
	s_waitcnt vmcnt(1)
	v_cmp_eq_u32_e32 vcc, 5, v245
	s_cbranch_vccnz .Lseam5_done
	s_add_i32 s100, s100, -1
	s_cmp_lg_u32 s100, 0
	s_cbranch_scc1 .Lseam5_poll
